# norm phase: split-K partial slices of context rows loaded with a 7-deep ring (one round trip) instead of two slices per round trip
# baseline (speedup 1.0000x reference)
; __device__ __forceinline__ void norm_phase(KP P, const float* g, const float* MODl, int shc, int scc, bool from_input, int npart) {
;     ...
;             if (row < M) { const int b = row / RPB, t = row - b * RPB, w = t >= SEQ ? 2 : b;
;                 if (t >= SEQ && npart > 0) {
;                     const float4* pp = (const float4*)(P->ws + WS_PART) + (size_t)(b * CTXL + (t - SEQ)) * 256 + lane;
;                     for (int q = 0; q < npart; ++q) {
.Lnm_fh0_wdone:
	s_cmp_ge_u32 s0, 0x2100
	s_cselect_b32 s6, 1, 0
	s_mul_i32 s7, s6, 0x2100
	s_sub_u32 s7, s0, s7
	s_cmp_ge_u32 s7, 0x2000
	s_cselect_b32 s30, 2, s6
	s_lshl_b32 s31, s0, 12
	s_add_u32 s64, s60, s31
	s_addc_u32 s65, s61, 0
	s_cmp_lt_u32 s7, 0x2000
	s_cbranch_scc1 .Lnm_fh0_nopart
	s_cmp_eq_u32 s3, 0
	s_cbranch_scc1 .Lnm_fh0_nopart
	s_lshl_b32 s6, s6, 8
	s_add_u32 s6, s6, s7
	s_sub_u32 s6, s6, 0x2000
	s_lshl_b32 s6, s6, 12
	s_add_u32 s10, s60, s6
	s_addc_u32 s11, s61, 0
	s_add_u32 s10, s10, 0x10e00000
	s_addc_u32 s11, s11, 0
	s_cmp_eq_u32 s3, 10
	s_cbranch_scc1 .Lnm_fh0_p10
	s_cmp_eq_u32 s3, 3
	s_cbranch_scc1 .Lnm_fh0_p3
	s_mov_b32 s31, s3

; __device__ __forceinline__ void norm_phase(KP P, const float* g, const float* MODl, int shc, int scc, bool from_input, int npart) {
;     ...
;                 if (t >= SEQ && npart > 0) {
;                     const float4* pp = (const float4*)(P->ws + WS_PART) + (size_t)(b * CTXL + (t - SEQ)) * 256 + lane;
;                     for (int q = 0; q < npart; ++q) {
; #pragma unroll
;                         for (int j = 0; j < 4; ++j) { const float4 a = pp[(size_t)q * 512 * 256 + 64 * j]; v[u][j].x += a.x; v[u][j].y += a.y; v[u][j].z += a.z; v[u][j].w += a.w; } } }
.Lnm_fh0_pone:
	s_cmp_eq_u32 s31, 0
	s_cbranch_scc1 .Lnm_fh0_pdone
	global_load_dwordx4 v[80:83], v112, s[10:11] offset:0
	global_load_dwordx4 v[84:87], v112, s[10:11] offset:1024
	global_load_dwordx4 v[88:91], v112, s[10:11] offset:2048
	global_load_dwordx4 v[92:95], v112, s[10:11] offset:3072
	s_waitcnt vmcnt(0)
	v_pk_add_f32 v[0:1], v[0:1], v[80:81]
	v_pk_add_f32 v[2:3], v[2:3], v[82:83]
	v_pk_add_f32 v[4:5], v[4:5], v[84:85]
	v_pk_add_f32 v[6:7], v[6:7], v[86:87]
	v_pk_add_f32 v[8:9], v[8:9], v[88:89]
	v_pk_add_f32 v[10:11], v[10:11], v[90:91]
	v_pk_add_f32 v[12:13], v[12:13], v[92:93]
	v_pk_add_f32 v[14:15], v[14:15], v[94:95]
	s_branch .Lnm_fh0_pdone
.Lnm_fh0_p10:
	global_load_dwordx4 v[80:83], v112, s[10:11] offset:0
	global_load_dwordx4 v[84:87], v112, s[10:11] offset:1024
	global_load_dwordx4 v[88:91], v112, s[10:11] offset:2048
	global_load_dwordx4 v[92:95], v112, s[10:11] offset:3072
	s_add_u32 s6, s10, 0x200000
	s_addc_u32 s7, s11, 0
	global_load_dwordx4 v[96:99], v112, s[6:7] offset:0
	global_load_dwordx4 v[100:103], v112, s[6:7] offset:1024
	global_load_dwordx4 v[104:107], v112, s[6:7] offset:2048
	global_load_dwordx4 v[108:111], v112, s[6:7] offset:3072
	s_add_u32 s6, s10, 0x400000
	s_addc_u32 s7, s11, 0
	global_load_dwordx4 v[128:131], v112, s[6:7] offset:0
	global_load_dwordx4 v[132:135], v112, s[6:7] offset:1024
	global_load_dwordx4 v[136:139], v112, s[6:7] offset:2048
	global_load_dwordx4 v[140:143], v112, s[6:7] offset:3072
	s_add_u32 s6, s10, 0x600000
	s_addc_u32 s7, s11, 0
	global_load_dwordx4 v[144:147], v112, s[6:7] offset:0
	global_load_dwordx4 v[148:151], v112, s[6:7] offset:1024
	global_load_dwordx4 v[152:155], v112, s[6:7] offset:2048
	global_load_dwordx4 v[156:159], v112, s[6:7] offset:3072
	s_add_u32 s6, s10, 0x800000
	s_addc_u32 s7, s11, 0
	global_load_dwordx4 v[170:173], v112, s[6:7] offset:0
	global_load_dwordx4 v[174:177], v112, s[6:7] offset:1024
	global_load_dwordx4 v[178:181], v112, s[6:7] offset:2048
	global_load_dwordx4 v[182:185], v112, s[6:7] offset:3072
	s_add_u32 s6, s10, 0xa00000
	s_addc_u32 s7, s11, 0
	global_load_dwordx4 v[200:203], v112, s[6:7] offset:0
	global_load_dwordx4 v[204:207], v112, s[6:7] offset:1024
	global_load_dwordx4 v[208:211], v112, s[6:7] offset:2048
	global_load_dwordx4 v[212:215], v112, s[6:7] offset:3072
	s_add_u32 s6, s10, 0xc00000
	s_addc_u32 s7, s11, 0
	global_load_dwordx4 v[226:229], v112, s[6:7] offset:0
	global_load_dwordx4 v[230:233], v112, s[6:7] offset:1024
	global_load_dwordx4 v[234:237], v112, s[6:7] offset:2048
	global_load_dwordx4 v[238:241], v112, s[6:7] offset:3072
	s_waitcnt vmcnt(24)
	v_pk_add_f32 v[0:1], v[0:1], v[80:81]
	v_pk_add_f32 v[2:3], v[2:3], v[82:83]
	v_pk_add_f32 v[4:5], v[4:5], v[84:85]
	v_pk_add_f32 v[6:7], v[6:7], v[86:87]
	v_pk_add_f32 v[8:9], v[8:9], v[88:89]
	v_pk_add_f32 v[10:11], v[10:11], v[90:91]
	v_pk_add_f32 v[12:13], v[12:13], v[92:93]
	v_pk_add_f32 v[14:15], v[14:15], v[94:95]
	s_add_u32 s6, s10, 0xe00000
	s_addc_u32 s7, s11, 0
	global_load_dwordx4 v[80:83], v112, s[6:7] offset:0
	global_load_dwordx4 v[84:87], v112, s[6:7] offset:1024
	global_load_dwordx4 v[88:91], v112, s[6:7] offset:2048
	global_load_dwordx4 v[92:95], v112, s[6:7] offset:3072
	s_waitcnt vmcnt(24)
	v_pk_add_f32 v[0:1], v[0:1], v[96:97]
	v_pk_add_f32 v[2:3], v[2:3], v[98:99]
	v_pk_add_f32 v[4:5], v[4:5], v[100:101]
	v_pk_add_f32 v[6:7], v[6:7], v[102:103]
	v_pk_add_f32 v[8:9], v[8:9], v[104:105]
	v_pk_add_f32 v[10:11], v[10:11], v[106:107]
	v_pk_add_f32 v[12:13], v[12:13], v[108:109]
	v_pk_add_f32 v[14:15], v[14:15], v[110:111]
	s_add_u32 s6, s10, 0x1000000
	s_addc_u32 s7, s11, 0
	global_load_dwordx4 v[96:99], v112, s[6:7] offset:0
	global_load_dwordx4 v[100:103], v112, s[6:7] offset:1024
	global_load_dwordx4 v[104:107], v112, s[6:7] offset:2048
	global_load_dwordx4 v[108:111], v112, s[6:7] offset:3072
	s_waitcnt vmcnt(24)
	v_pk_add_f32 v[0:1], v[0:1], v[128:129]
	v_pk_add_f32 v[2:3], v[2:3], v[130:131]
	v_pk_add_f32 v[4:5], v[4:5], v[132:133]
	v_pk_add_f32 v[6:7], v[6:7], v[134:135]
	v_pk_add_f32 v[8:9], v[8:9], v[136:137]
	v_pk_add_f32 v[10:11], v[10:11], v[138:139]
	v_pk_add_f32 v[12:13], v[12:13], v[140:141]
	v_pk_add_f32 v[14:15], v[14:15], v[142:143]
	s_add_u32 s6, s10, 0x1200000
	s_addc_u32 s7, s11, 0
	global_load_dwordx4 v[128:131], v112, s[6:7] offset:0
	global_load_dwordx4 v[132:135], v112, s[6:7] offset:1024
	global_load_dwordx4 v[136:139], v112, s[6:7] offset:2048
	global_load_dwordx4 v[140:143], v112, s[6:7] offset:3072
	s_waitcnt vmcnt(24)
	v_pk_add_f32 v[0:1], v[0:1], v[144:145]
	v_pk_add_f32 v[2:3], v[2:3], v[146:147]
	v_pk_add_f32 v[4:5], v[4:5], v[148:149]
	v_pk_add_f32 v[6:7], v[6:7], v[150:151]
	v_pk_add_f32 v[8:9], v[8:9], v[152:153]
	v_pk_add_f32 v[10:11], v[10:11], v[154:155]
	v_pk_add_f32 v[12:13], v[12:13], v[156:157]
	v_pk_add_f32 v[14:15], v[14:15], v[158:159]
	s_waitcnt vmcnt(20)
	v_pk_add_f32 v[0:1], v[0:1], v[170:171]
	v_pk_add_f32 v[2:3], v[2:3], v[172:173]
	v_pk_add_f32 v[4:5], v[4:5], v[174:175]
	v_pk_add_f32 v[6:7], v[6:7], v[176:177]
	v_pk_add_f32 v[8:9], v[8:9], v[178:179]
	v_pk_add_f32 v[10:11], v[10:11], v[180:181]
	v_pk_add_f32 v[12:13], v[12:13], v[182:183]
	v_pk_add_f32 v[14:15], v[14:15], v[184:185]
	s_waitcnt vmcnt(16)
	v_pk_add_f32 v[0:1], v[0:1], v[200:201]
	v_pk_add_f32 v[2:3], v[2:3], v[202:203]
	v_pk_add_f32 v[4:5], v[4:5], v[204:205]
	v_pk_add_f32 v[6:7], v[6:7], v[206:207]
	v_pk_add_f32 v[8:9], v[8:9], v[208:209]
	v_pk_add_f32 v[10:11], v[10:11], v[210:211]
	v_pk_add_f32 v[12:13], v[12:13], v[212:213]
	v_pk_add_f32 v[14:15], v[14:15], v[214:215]
	s_waitcnt vmcnt(12)
	v_pk_add_f32 v[0:1], v[0:1], v[226:227]
	v_pk_add_f32 v[2:3], v[2:3], v[228:229]
	v_pk_add_f32 v[4:5], v[4:5], v[230:231]
	v_pk_add_f32 v[6:7], v[6:7], v[232:233]
	v_pk_add_f32 v[8:9], v[8:9], v[234:235]
	v_pk_add_f32 v[10:11], v[10:11], v[236:237]
	v_pk_add_f32 v[12:13], v[12:13], v[238:239]
	v_pk_add_f32 v[14:15], v[14:15], v[240:241]
	s_waitcnt vmcnt(8)
	v_pk_add_f32 v[0:1], v[0:1], v[80:81]
	v_pk_add_f32 v[2:3], v[2:3], v[82:83]
	v_pk_add_f32 v[4:5], v[4:5], v[84:85]
	v_pk_add_f32 v[6:7], v[6:7], v[86:87]
	v_pk_add_f32 v[8:9], v[8:9], v[88:89]
	v_pk_add_f32 v[10:11], v[10:11], v[90:91]
	v_pk_add_f32 v[12:13], v[12:13], v[92:93]
	v_pk_add_f32 v[14:15], v[14:15], v[94:95]
	s_waitcnt vmcnt(4)
	v_pk_add_f32 v[0:1], v[0:1], v[96:97]
	v_pk_add_f32 v[2:3], v[2:3], v[98:99]
	v_pk_add_f32 v[4:5], v[4:5], v[100:101]
	v_pk_add_f32 v[6:7], v[6:7], v[102:103]
	v_pk_add_f32 v[8:9], v[8:9], v[104:105]
	v_pk_add_f32 v[10:11], v[10:11], v[106:107]
	v_pk_add_f32 v[12:13], v[12:13], v[108:109]
	v_pk_add_f32 v[14:15], v[14:15], v[110:111]
	s_waitcnt vmcnt(0)
	v_pk_add_f32 v[0:1], v[0:1], v[128:129]
	v_pk_add_f32 v[2:3], v[2:3], v[130:131]
	v_pk_add_f32 v[4:5], v[4:5], v[132:133]
	v_pk_add_f32 v[6:7], v[6:7], v[134:135]
	v_pk_add_f32 v[8:9], v[8:9], v[136:137]
	v_pk_add_f32 v[10:11], v[10:11], v[138:139]
	v_pk_add_f32 v[12:13], v[12:13], v[140:141]
	v_pk_add_f32 v[14:15], v[14:15], v[142:143]
	s_branch .Lnm_fh0_pdone
; __device__ __forceinline__ void norm_phase(KP P, const float* g, const float* MODl, int shc, int scc, bool from_input, int npart) {
;     ...
;                     for (int q = 0; q < npart; ++q) {
; #pragma unroll
;                         for (int j = 0; j < 4; ++j) { const float4 a = pp[(size_t)q * 512 * 256 + 64 * j]; v[u][j].x += a.x; v[u][j].y += a.y; v[u][j].z += a.z; v[u][j].w += a.w; } } }
.Lnm_fh0_p3:
	global_load_dwordx4 v[80:83], v112, s[10:11] offset:0
	global_load_dwordx4 v[84:87], v112, s[10:11] offset:1024
	global_load_dwordx4 v[88:91], v112, s[10:11] offset:2048
	global_load_dwordx4 v[92:95], v112, s[10:11] offset:3072
	s_add_u32 s6, s10, 0x200000
	s_addc_u32 s7, s11, 0
	global_load_dwordx4 v[96:99], v112, s[6:7] offset:0
	global_load_dwordx4 v[100:103], v112, s[6:7] offset:1024
	global_load_dwordx4 v[104:107], v112, s[6:7] offset:2048
	global_load_dwordx4 v[108:111], v112, s[6:7] offset:3072
	s_add_u32 s6, s10, 0x400000
	s_addc_u32 s7, s11, 0
	global_load_dwordx4 v[128:131], v112, s[6:7] offset:0
	global_load_dwordx4 v[132:135], v112, s[6:7] offset:1024
	global_load_dwordx4 v[136:139], v112, s[6:7] offset:2048
	global_load_dwordx4 v[140:143], v112, s[6:7] offset:3072
	s_waitcnt vmcnt(8)
	v_pk_add_f32 v[0:1], v[0:1], v[80:81]
	v_pk_add_f32 v[2:3], v[2:3], v[82:83]
	v_pk_add_f32 v[4:5], v[4:5], v[84:85]
	v_pk_add_f32 v[6:7], v[6:7], v[86:87]
	v_pk_add_f32 v[8:9], v[8:9], v[88:89]
	v_pk_add_f32 v[10:11], v[10:11], v[90:91]
	v_pk_add_f32 v[12:13], v[12:13], v[92:93]
	v_pk_add_f32 v[14:15], v[14:15], v[94:95]
	s_waitcnt vmcnt(4)
	v_pk_add_f32 v[0:1], v[0:1], v[96:97]
	v_pk_add_f32 v[2:3], v[2:3], v[98:99]
	v_pk_add_f32 v[4:5], v[4:5], v[100:101]
	v_pk_add_f32 v[6:7], v[6:7], v[102:103]
	v_pk_add_f32 v[8:9], v[8:9], v[104:105]
	v_pk_add_f32 v[10:11], v[10:11], v[106:107]
	v_pk_add_f32 v[12:13], v[12:13], v[108:109]
	v_pk_add_f32 v[14:15], v[14:15], v[110:111]
	s_waitcnt vmcnt(0)
	v_pk_add_f32 v[0:1], v[0:1], v[128:129]
	v_pk_add_f32 v[2:3], v[2:3], v[130:131]
	v_pk_add_f32 v[4:5], v[4:5], v[132:133]
	v_pk_add_f32 v[6:7], v[6:7], v[134:135]
	v_pk_add_f32 v[8:9], v[8:9], v[136:137]
	v_pk_add_f32 v[10:11], v[10:11], v[138:139]
	v_pk_add_f32 v[12:13], v[12:13], v[140:141]
	v_pk_add_f32 v[14:15], v[14:15], v[142:143]

; __device__ __forceinline__ void norm_phase(KP P, const float* g, const float* MODl, int shc, int scc, bool from_input, int npart) {
;     ...
;                 if (t >= SEQ && npart > 0) {
;                     const float4* pp = (const float4*)(P->ws + WS_PART) + (size_t)(b * CTXL + (t - SEQ)) * 256 + lane;
;                     for (int q = 0; q < npart; ++q) {
; #pragma unroll
;                         for (int j = 0; j < 4; ++j) { const float4 a = pp[(size_t)q * 512 * 256 + 64 * j]; v[u][j].x += a.x; v[u][j].y += a.y; v[u][j].z += a.z; v[u][j].w += a.w; } } }
.Lnm_fh1_pone:
	s_cmp_eq_u32 s31, 0
	s_cbranch_scc1 .Lnm_fh1_pdone
	global_load_dwordx4 v[80:83], v112, s[10:11] offset:0
	global_load_dwordx4 v[84:87], v112, s[10:11] offset:1024
	global_load_dwordx4 v[88:91], v112, s[10:11] offset:2048
	global_load_dwordx4 v[92:95], v112, s[10:11] offset:3072
	s_waitcnt vmcnt(0)
	v_pk_add_f32 v[16:17], v[16:17], v[80:81]
	v_pk_add_f32 v[18:19], v[18:19], v[82:83]
	v_pk_add_f32 v[20:21], v[20:21], v[84:85]
	v_pk_add_f32 v[22:23], v[22:23], v[86:87]
	v_pk_add_f32 v[24:25], v[24:25], v[88:89]
	v_pk_add_f32 v[26:27], v[26:27], v[90:91]
	v_pk_add_f32 v[28:29], v[28:29], v[92:93]
	v_pk_add_f32 v[30:31], v[30:31], v[94:95]
	s_branch .Lnm_fh1_pdone
.Lnm_fh1_p10:
	global_load_dwordx4 v[80:83], v112, s[10:11] offset:0
	global_load_dwordx4 v[84:87], v112, s[10:11] offset:1024
	global_load_dwordx4 v[88:91], v112, s[10:11] offset:2048
	global_load_dwordx4 v[92:95], v112, s[10:11] offset:3072
	s_add_u32 s6, s10, 0x200000
	s_addc_u32 s7, s11, 0
	global_load_dwordx4 v[96:99], v112, s[6:7] offset:0
	global_load_dwordx4 v[100:103], v112, s[6:7] offset:1024
	global_load_dwordx4 v[104:107], v112, s[6:7] offset:2048
	global_load_dwordx4 v[108:111], v112, s[6:7] offset:3072
	s_add_u32 s6, s10, 0x400000
	s_addc_u32 s7, s11, 0
	global_load_dwordx4 v[128:131], v112, s[6:7] offset:0
	global_load_dwordx4 v[132:135], v112, s[6:7] offset:1024
	global_load_dwordx4 v[136:139], v112, s[6:7] offset:2048
	global_load_dwordx4 v[140:143], v112, s[6:7] offset:3072
	s_add_u32 s6, s10, 0x600000
	s_addc_u32 s7, s11, 0
	global_load_dwordx4 v[144:147], v112, s[6:7] offset:0
	global_load_dwordx4 v[148:151], v112, s[6:7] offset:1024
	global_load_dwordx4 v[152:155], v112, s[6:7] offset:2048
	global_load_dwordx4 v[156:159], v112, s[6:7] offset:3072
	s_add_u32 s6, s10, 0x800000
	s_addc_u32 s7, s11, 0
	global_load_dwordx4 v[170:173], v112, s[6:7] offset:0
	global_load_dwordx4 v[174:177], v112, s[6:7] offset:1024
	global_load_dwordx4 v[178:181], v112, s[6:7] offset:2048
	global_load_dwordx4 v[182:185], v112, s[6:7] offset:3072
	s_add_u32 s6, s10, 0xa00000
	s_addc_u32 s7, s11, 0
	global_load_dwordx4 v[200:203], v112, s[6:7] offset:0
	global_load_dwordx4 v[204:207], v112, s[6:7] offset:1024
	global_load_dwordx4 v[208:211], v112, s[6:7] offset:2048
	global_load_dwordx4 v[212:215], v112, s[6:7] offset:3072
	s_add_u32 s6, s10, 0xc00000
	s_addc_u32 s7, s11, 0
	global_load_dwordx4 v[226:229], v112, s[6:7] offset:0
	global_load_dwordx4 v[230:233], v112, s[6:7] offset:1024
	global_load_dwordx4 v[234:237], v112, s[6:7] offset:2048
	global_load_dwordx4 v[238:241], v112, s[6:7] offset:3072
	s_waitcnt vmcnt(24)
	v_pk_add_f32 v[16:17], v[16:17], v[80:81]
	v_pk_add_f32 v[18:19], v[18:19], v[82:83]
	v_pk_add_f32 v[20:21], v[20:21], v[84:85]
	v_pk_add_f32 v[22:23], v[22:23], v[86:87]
	v_pk_add_f32 v[24:25], v[24:25], v[88:89]
	v_pk_add_f32 v[26:27], v[26:27], v[90:91]
	v_pk_add_f32 v[28:29], v[28:29], v[92:93]
	v_pk_add_f32 v[30:31], v[30:31], v[94:95]
	s_add_u32 s6, s10, 0xe00000
	s_addc_u32 s7, s11, 0
	global_load_dwordx4 v[80:83], v112, s[6:7] offset:0
	global_load_dwordx4 v[84:87], v112, s[6:7] offset:1024
	global_load_dwordx4 v[88:91], v112, s[6:7] offset:2048
	global_load_dwordx4 v[92:95], v112, s[6:7] offset:3072
	s_waitcnt vmcnt(24)
	v_pk_add_f32 v[16:17], v[16:17], v[96:97]
	v_pk_add_f32 v[18:19], v[18:19], v[98:99]
	v_pk_add_f32 v[20:21], v[20:21], v[100:101]
	v_pk_add_f32 v[22:23], v[22:23], v[102:103]
	v_pk_add_f32 v[24:25], v[24:25], v[104:105]
	v_pk_add_f32 v[26:27], v[26:27], v[106:107]
	v_pk_add_f32 v[28:29], v[28:29], v[108:109]
	v_pk_add_f32 v[30:31], v[30:31], v[110:111]
	s_add_u32 s6, s10, 0x1000000
	s_addc_u32 s7, s11, 0
	global_load_dwordx4 v[96:99], v112, s[6:7] offset:0
	global_load_dwordx4 v[100:103], v112, s[6:7] offset:1024
	global_load_dwordx4 v[104:107], v112, s[6:7] offset:2048
	global_load_dwordx4 v[108:111], v112, s[6:7] offset:3072
	s_waitcnt vmcnt(24)
	v_pk_add_f32 v[16:17], v[16:17], v[128:129]
	v_pk_add_f32 v[18:19], v[18:19], v[130:131]
	v_pk_add_f32 v[20:21], v[20:21], v[132:133]
	v_pk_add_f32 v[22:23], v[22:23], v[134:135]
	v_pk_add_f32 v[24:25], v[24:25], v[136:137]
	v_pk_add_f32 v[26:27], v[26:27], v[138:139]
	v_pk_add_f32 v[28:29], v[28:29], v[140:141]
	v_pk_add_f32 v[30:31], v[30:31], v[142:143]
	s_add_u32 s6, s10, 0x1200000
	s_addc_u32 s7, s11, 0
	global_load_dwordx4 v[128:131], v112, s[6:7] offset:0
	global_load_dwordx4 v[132:135], v112, s[6:7] offset:1024
	global_load_dwordx4 v[136:139], v112, s[6:7] offset:2048
	global_load_dwordx4 v[140:143], v112, s[6:7] offset:3072
	s_waitcnt vmcnt(24)
; __device__ __forceinline__ void norm_phase(KP P, const float* g, const float* MODl, int shc, int scc, bool from_input, int npart) {
;     ...
;                 if (t >= SEQ && npart > 0) {
;                     const float4* pp = (const float4*)(P->ws + WS_PART) + (size_t)(b * CTXL + (t - SEQ)) * 256 + lane;
;                     for (int q = 0; q < npart; ++q) {
; #pragma unroll
;                         for (int j = 0; j < 4; ++j) { const float4 a = pp[(size_t)q * 512 * 256 + 64 * j]; v[u][j].x += a.x; v[u][j].y += a.y; v[u][j].z += a.z; v[u][j].w += a.w; } } }
	v_pk_add_f32 v[16:17], v[16:17], v[144:145]
	v_pk_add_f32 v[18:19], v[18:19], v[146:147]
	v_pk_add_f32 v[20:21], v[20:21], v[148:149]
	v_pk_add_f32 v[22:23], v[22:23], v[150:151]
	v_pk_add_f32 v[24:25], v[24:25], v[152:153]
	v_pk_add_f32 v[26:27], v[26:27], v[154:155]
	v_pk_add_f32 v[28:29], v[28:29], v[156:157]
	v_pk_add_f32 v[30:31], v[30:31], v[158:159]
	s_waitcnt vmcnt(20)
	v_pk_add_f32 v[16:17], v[16:17], v[170:171]
	v_pk_add_f32 v[18:19], v[18:19], v[172:173]
	v_pk_add_f32 v[20:21], v[20:21], v[174:175]
	v_pk_add_f32 v[22:23], v[22:23], v[176:177]
	v_pk_add_f32 v[24:25], v[24:25], v[178:179]
	v_pk_add_f32 v[26:27], v[26:27], v[180:181]
	v_pk_add_f32 v[28:29], v[28:29], v[182:183]
	v_pk_add_f32 v[30:31], v[30:31], v[184:185]
	s_waitcnt vmcnt(16)
	v_pk_add_f32 v[16:17], v[16:17], v[200:201]
	v_pk_add_f32 v[18:19], v[18:19], v[202:203]
	v_pk_add_f32 v[20:21], v[20:21], v[204:205]
	v_pk_add_f32 v[22:23], v[22:23], v[206:207]
	v_pk_add_f32 v[24:25], v[24:25], v[208:209]
	v_pk_add_f32 v[26:27], v[26:27], v[210:211]
	v_pk_add_f32 v[28:29], v[28:29], v[212:213]
	v_pk_add_f32 v[30:31], v[30:31], v[214:215]
	s_waitcnt vmcnt(12)
	v_pk_add_f32 v[16:17], v[16:17], v[226:227]
	v_pk_add_f32 v[18:19], v[18:19], v[228:229]
	v_pk_add_f32 v[20:21], v[20:21], v[230:231]
	v_pk_add_f32 v[22:23], v[22:23], v[232:233]
	v_pk_add_f32 v[24:25], v[24:25], v[234:235]
	v_pk_add_f32 v[26:27], v[26:27], v[236:237]
	v_pk_add_f32 v[28:29], v[28:29], v[238:239]
	v_pk_add_f32 v[30:31], v[30:31], v[240:241]
	s_waitcnt vmcnt(8)
	v_pk_add_f32 v[16:17], v[16:17], v[80:81]
	v_pk_add_f32 v[18:19], v[18:19], v[82:83]
	v_pk_add_f32 v[20:21], v[20:21], v[84:85]
	v_pk_add_f32 v[22:23], v[22:23], v[86:87]
	v_pk_add_f32 v[24:25], v[24:25], v[88:89]
	v_pk_add_f32 v[26:27], v[26:27], v[90:91]
	v_pk_add_f32 v[28:29], v[28:29], v[92:93]
	v_pk_add_f32 v[30:31], v[30:31], v[94:95]
	s_waitcnt vmcnt(4)
	v_pk_add_f32 v[16:17], v[16:17], v[96:97]
	v_pk_add_f32 v[18:19], v[18:19], v[98:99]
	v_pk_add_f32 v[20:21], v[20:21], v[100:101]
	v_pk_add_f32 v[22:23], v[22:23], v[102:103]
	v_pk_add_f32 v[24:25], v[24:25], v[104:105]
	v_pk_add_f32 v[26:27], v[26:27], v[106:107]
	v_pk_add_f32 v[28:29], v[28:29], v[108:109]
	v_pk_add_f32 v[30:31], v[30:31], v[110:111]
	s_waitcnt vmcnt(0)
	v_pk_add_f32 v[16:17], v[16:17], v[128:129]
	v_pk_add_f32 v[18:19], v[18:19], v[130:131]
	v_pk_add_f32 v[20:21], v[20:21], v[132:133]
	v_pk_add_f32 v[22:23], v[22:23], v[134:135]
	v_pk_add_f32 v[24:25], v[24:25], v[136:137]
	v_pk_add_f32 v[26:27], v[26:27], v[138:139]
	v_pk_add_f32 v[28:29], v[28:29], v[140:141]
	v_pk_add_f32 v[30:31], v[30:31], v[142:143]
	s_branch .Lnm_fh1_pdone
.Lnm_fh1_p3:
	global_load_dwordx4 v[80:83], v112, s[10:11] offset:0
	global_load_dwordx4 v[84:87], v112, s[10:11] offset:1024
	global_load_dwordx4 v[88:91], v112, s[10:11] offset:2048
	global_load_dwordx4 v[92:95], v112, s[10:11] offset:3072
	s_add_u32 s6, s10, 0x200000
	s_addc_u32 s7, s11, 0
	global_load_dwordx4 v[96:99], v112, s[6:7] offset:0
	global_load_dwordx4 v[100:103], v112, s[6:7] offset:1024
	global_load_dwordx4 v[104:107], v112, s[6:7] offset:2048
	global_load_dwordx4 v[108:111], v112, s[6:7] offset:3072
	s_add_u32 s6, s10, 0x400000
	s_addc_u32 s7, s11, 0
	global_load_dwordx4 v[128:131], v112, s[6:7] offset:0
	global_load_dwordx4 v[132:135], v112, s[6:7] offset:1024
	global_load_dwordx4 v[136:139], v112, s[6:7] offset:2048
	global_load_dwordx4 v[140:143], v112, s[6:7] offset:3072
	s_waitcnt vmcnt(8)
	v_pk_add_f32 v[16:17], v[16:17], v[80:81]
	v_pk_add_f32 v[18:19], v[18:19], v[82:83]
	v_pk_add_f32 v[20:21], v[20:21], v[84:85]
	v_pk_add_f32 v[22:23], v[22:23], v[86:87]
	v_pk_add_f32 v[24:25], v[24:25], v[88:89]
	v_pk_add_f32 v[26:27], v[26:27], v[90:91]
	v_pk_add_f32 v[28:29], v[28:29], v[92:93]
	v_pk_add_f32 v[30:31], v[30:31], v[94:95]
	s_waitcnt vmcnt(4)
	v_pk_add_f32 v[16:17], v[16:17], v[96:97]
	v_pk_add_f32 v[18:19], v[18:19], v[98:99]
	v_pk_add_f32 v[20:21], v[20:21], v[100:101]
	v_pk_add_f32 v[22:23], v[22:23], v[102:103]
	v_pk_add_f32 v[24:25], v[24:25], v[104:105]
	v_pk_add_f32 v[26:27], v[26:27], v[106:107]
	v_pk_add_f32 v[28:29], v[28:29], v[108:109]
	v_pk_add_f32 v[30:31], v[30:31], v[110:111]
	s_waitcnt vmcnt(0)
	v_pk_add_f32 v[16:17], v[16:17], v[128:129]
	v_pk_add_f32 v[18:19], v[18:19], v[130:131]
	v_pk_add_f32 v[20:21], v[20:21], v[132:133]
	v_pk_add_f32 v[22:23], v[22:23], v[134:135]
	v_pk_add_f32 v[24:25], v[24:25], v[136:137]
	v_pk_add_f32 v[26:27], v[26:27], v[138:139]
	v_pk_add_f32 v[28:29], v[28:29], v[140:141]
	v_pk_add_f32 v[30:31], v[30:31], v[142:143]

; __device__ __forceinline__ void norm_phase(KP P, const float* g, const float* MODl, int shc, int scc, bool from_input, int npart) {
;     ...
;                 if (t >= SEQ && npart > 0) {
;                     const float4* pp = (const float4*)(P->ws + WS_PART) + (size_t)(b * CTXL + (t - SEQ)) * 256 + lane;
;                     for (int q = 0; q < npart; ++q) {
; #pragma unroll
;                         for (int j = 0; j < 4; ++j) { const float4 a = pp[(size_t)q * 512 * 256 + 64 * j]; v[u][j].x += a.x; v[u][j].y += a.y; v[u][j].z += a.z; v[u][j].w += a.w; } } }
.Lnm_fh2_pone:
	s_cmp_eq_u32 s31, 0
	s_cbranch_scc1 .Lnm_fh2_pdone
	global_load_dwordx4 v[80:83], v112, s[10:11] offset:0
	global_load_dwordx4 v[84:87], v112, s[10:11] offset:1024
	global_load_dwordx4 v[88:91], v112, s[10:11] offset:2048
	global_load_dwordx4 v[92:95], v112, s[10:11] offset:3072
	s_waitcnt vmcnt(0)
	v_pk_add_f32 v[32:33], v[32:33], v[80:81]
	v_pk_add_f32 v[34:35], v[34:35], v[82:83]
	v_pk_add_f32 v[36:37], v[36:37], v[84:85]
	v_pk_add_f32 v[38:39], v[38:39], v[86:87]
	v_pk_add_f32 v[40:41], v[40:41], v[88:89]
	v_pk_add_f32 v[42:43], v[42:43], v[90:91]
	v_pk_add_f32 v[44:45], v[44:45], v[92:93]
	v_pk_add_f32 v[46:47], v[46:47], v[94:95]
	s_branch .Lnm_fh2_pdone
.Lnm_fh2_p10:
	global_load_dwordx4 v[80:83], v112, s[10:11] offset:0
	global_load_dwordx4 v[84:87], v112, s[10:11] offset:1024
	global_load_dwordx4 v[88:91], v112, s[10:11] offset:2048
	global_load_dwordx4 v[92:95], v112, s[10:11] offset:3072
	s_add_u32 s6, s10, 0x200000
	s_addc_u32 s7, s11, 0
	global_load_dwordx4 v[96:99], v112, s[6:7] offset:0
	global_load_dwordx4 v[100:103], v112, s[6:7] offset:1024
	global_load_dwordx4 v[104:107], v112, s[6:7] offset:2048
	global_load_dwordx4 v[108:111], v112, s[6:7] offset:3072
	s_add_u32 s6, s10, 0x400000
	s_addc_u32 s7, s11, 0
	global_load_dwordx4 v[128:131], v112, s[6:7] offset:0
	global_load_dwordx4 v[132:135], v112, s[6:7] offset:1024
	global_load_dwordx4 v[136:139], v112, s[6:7] offset:2048
	global_load_dwordx4 v[140:143], v112, s[6:7] offset:3072
	s_add_u32 s6, s10, 0x600000
	s_addc_u32 s7, s11, 0
	global_load_dwordx4 v[144:147], v112, s[6:7] offset:0
	global_load_dwordx4 v[148:151], v112, s[6:7] offset:1024
	global_load_dwordx4 v[152:155], v112, s[6:7] offset:2048
	global_load_dwordx4 v[156:159], v112, s[6:7] offset:3072
	s_add_u32 s6, s10, 0x800000
	s_addc_u32 s7, s11, 0
	global_load_dwordx4 v[170:173], v112, s[6:7] offset:0
	global_load_dwordx4 v[174:177], v112, s[6:7] offset:1024
	global_load_dwordx4 v[178:181], v112, s[6:7] offset:2048
	global_load_dwordx4 v[182:185], v112, s[6:7] offset:3072
	s_add_u32 s6, s10, 0xa00000
	s_addc_u32 s7, s11, 0
	global_load_dwordx4 v[200:203], v112, s[6:7] offset:0
	global_load_dwordx4 v[204:207], v112, s[6:7] offset:1024
	global_load_dwordx4 v[208:211], v112, s[6:7] offset:2048
	global_load_dwordx4 v[212:215], v112, s[6:7] offset:3072
	s_add_u32 s6, s10, 0xc00000
	s_addc_u32 s7, s11, 0
	global_load_dwordx4 v[226:229], v112, s[6:7] offset:0
	global_load_dwordx4 v[230:233], v112, s[6:7] offset:1024
	global_load_dwordx4 v[234:237], v112, s[6:7] offset:2048
	global_load_dwordx4 v[238:241], v112, s[6:7] offset:3072
	s_waitcnt vmcnt(24)
	v_pk_add_f32 v[32:33], v[32:33], v[80:81]
	v_pk_add_f32 v[34:35], v[34:35], v[82:83]
	v_pk_add_f32 v[36:37], v[36:37], v[84:85]
	v_pk_add_f32 v[38:39], v[38:39], v[86:87]
	v_pk_add_f32 v[40:41], v[40:41], v[88:89]
	v_pk_add_f32 v[42:43], v[42:43], v[90:91]
	v_pk_add_f32 v[44:45], v[44:45], v[92:93]
	v_pk_add_f32 v[46:47], v[46:47], v[94:95]
	s_add_u32 s6, s10, 0xe00000
	s_addc_u32 s7, s11, 0
	global_load_dwordx4 v[80:83], v112, s[6:7] offset:0
	global_load_dwordx4 v[84:87], v112, s[6:7] offset:1024
	global_load_dwordx4 v[88:91], v112, s[6:7] offset:2048
	global_load_dwordx4 v[92:95], v112, s[6:7] offset:3072
	s_waitcnt vmcnt(24)
	v_pk_add_f32 v[32:33], v[32:33], v[96:97]
	v_pk_add_f32 v[34:35], v[34:35], v[98:99]
	v_pk_add_f32 v[36:37], v[36:37], v[100:101]
	v_pk_add_f32 v[38:39], v[38:39], v[102:103]
	v_pk_add_f32 v[40:41], v[40:41], v[104:105]
	v_pk_add_f32 v[42:43], v[42:43], v[106:107]
	v_pk_add_f32 v[44:45], v[44:45], v[108:109]
	v_pk_add_f32 v[46:47], v[46:47], v[110:111]
	s_add_u32 s6, s10, 0x1000000
	s_addc_u32 s7, s11, 0
	global_load_dwordx4 v[96:99], v112, s[6:7] offset:0
	global_load_dwordx4 v[100:103], v112, s[6:7] offset:1024
	global_load_dwordx4 v[104:107], v112, s[6:7] offset:2048
	global_load_dwordx4 v[108:111], v112, s[6:7] offset:3072
	s_waitcnt vmcnt(24)
	v_pk_add_f32 v[32:33], v[32:33], v[128:129]
	v_pk_add_f32 v[34:35], v[34:35], v[130:131]
	v_pk_add_f32 v[36:37], v[36:37], v[132:133]
	v_pk_add_f32 v[38:39], v[38:39], v[134:135]
	v_pk_add_f32 v[40:41], v[40:41], v[136:137]
	v_pk_add_f32 v[42:43], v[42:43], v[138:139]
	v_pk_add_f32 v[44:45], v[44:45], v[140:141]
	v_pk_add_f32 v[46:47], v[46:47], v[142:143]
	s_add_u32 s6, s10, 0x1200000
	s_addc_u32 s7, s11, 0
	global_load_dwordx4 v[128:131], v112, s[6:7] offset:0
	global_load_dwordx4 v[132:135], v112, s[6:7] offset:1024
	global_load_dwordx4 v[136:139], v112, s[6:7] offset:2048
	global_load_dwordx4 v[140:143], v112, s[6:7] offset:3072
	s_waitcnt vmcnt(24)
; __device__ __forceinline__ void norm_phase(KP P, const float* g, const float* MODl, int shc, int scc, bool from_input, int npart) {
;     ...
;                 if (t >= SEQ && npart > 0) {
;                     const float4* pp = (const float4*)(P->ws + WS_PART) + (size_t)(b * CTXL + (t - SEQ)) * 256 + lane;
;                     for (int q = 0; q < npart; ++q) {
; #pragma unroll
;                         for (int j = 0; j < 4; ++j) { const float4 a = pp[(size_t)q * 512 * 256 + 64 * j]; v[u][j].x += a.x; v[u][j].y += a.y; v[u][j].z += a.z; v[u][j].w += a.w; } } }
	v_pk_add_f32 v[32:33], v[32:33], v[144:145]
	v_pk_add_f32 v[34:35], v[34:35], v[146:147]
	v_pk_add_f32 v[36:37], v[36:37], v[148:149]
	v_pk_add_f32 v[38:39], v[38:39], v[150:151]
	v_pk_add_f32 v[40:41], v[40:41], v[152:153]
	v_pk_add_f32 v[42:43], v[42:43], v[154:155]
	v_pk_add_f32 v[44:45], v[44:45], v[156:157]
	v_pk_add_f32 v[46:47], v[46:47], v[158:159]
	s_waitcnt vmcnt(20)
	v_pk_add_f32 v[32:33], v[32:33], v[170:171]
	v_pk_add_f32 v[34:35], v[34:35], v[172:173]
	v_pk_add_f32 v[36:37], v[36:37], v[174:175]
	v_pk_add_f32 v[38:39], v[38:39], v[176:177]
	v_pk_add_f32 v[40:41], v[40:41], v[178:179]
	v_pk_add_f32 v[42:43], v[42:43], v[180:181]
	v_pk_add_f32 v[44:45], v[44:45], v[182:183]
	v_pk_add_f32 v[46:47], v[46:47], v[184:185]
	s_waitcnt vmcnt(16)
	v_pk_add_f32 v[32:33], v[32:33], v[200:201]
	v_pk_add_f32 v[34:35], v[34:35], v[202:203]
	v_pk_add_f32 v[36:37], v[36:37], v[204:205]
	v_pk_add_f32 v[38:39], v[38:39], v[206:207]
	v_pk_add_f32 v[40:41], v[40:41], v[208:209]
	v_pk_add_f32 v[42:43], v[42:43], v[210:211]
	v_pk_add_f32 v[44:45], v[44:45], v[212:213]
	v_pk_add_f32 v[46:47], v[46:47], v[214:215]
	s_waitcnt vmcnt(12)
	v_pk_add_f32 v[32:33], v[32:33], v[226:227]
	v_pk_add_f32 v[34:35], v[34:35], v[228:229]
	v_pk_add_f32 v[36:37], v[36:37], v[230:231]
	v_pk_add_f32 v[38:39], v[38:39], v[232:233]
	v_pk_add_f32 v[40:41], v[40:41], v[234:235]
	v_pk_add_f32 v[42:43], v[42:43], v[236:237]
	v_pk_add_f32 v[44:45], v[44:45], v[238:239]
	v_pk_add_f32 v[46:47], v[46:47], v[240:241]
	s_waitcnt vmcnt(8)
	v_pk_add_f32 v[32:33], v[32:33], v[80:81]
	v_pk_add_f32 v[34:35], v[34:35], v[82:83]
	v_pk_add_f32 v[36:37], v[36:37], v[84:85]
	v_pk_add_f32 v[38:39], v[38:39], v[86:87]
	v_pk_add_f32 v[40:41], v[40:41], v[88:89]
	v_pk_add_f32 v[42:43], v[42:43], v[90:91]
	v_pk_add_f32 v[44:45], v[44:45], v[92:93]
	v_pk_add_f32 v[46:47], v[46:47], v[94:95]
	s_waitcnt vmcnt(4)
	v_pk_add_f32 v[32:33], v[32:33], v[96:97]
	v_pk_add_f32 v[34:35], v[34:35], v[98:99]
	v_pk_add_f32 v[36:37], v[36:37], v[100:101]
	v_pk_add_f32 v[38:39], v[38:39], v[102:103]
	v_pk_add_f32 v[40:41], v[40:41], v[104:105]
	v_pk_add_f32 v[42:43], v[42:43], v[106:107]
	v_pk_add_f32 v[44:45], v[44:45], v[108:109]
	v_pk_add_f32 v[46:47], v[46:47], v[110:111]
	s_waitcnt vmcnt(0)
	v_pk_add_f32 v[32:33], v[32:33], v[128:129]
	v_pk_add_f32 v[34:35], v[34:35], v[130:131]
	v_pk_add_f32 v[36:37], v[36:37], v[132:133]
	v_pk_add_f32 v[38:39], v[38:39], v[134:135]
	v_pk_add_f32 v[40:41], v[40:41], v[136:137]
	v_pk_add_f32 v[42:43], v[42:43], v[138:139]
	v_pk_add_f32 v[44:45], v[44:45], v[140:141]
	v_pk_add_f32 v[46:47], v[46:47], v[142:143]
	s_branch .Lnm_fh2_pdone
.Lnm_fh2_p3:
	global_load_dwordx4 v[80:83], v112, s[10:11] offset:0
	global_load_dwordx4 v[84:87], v112, s[10:11] offset:1024
	global_load_dwordx4 v[88:91], v112, s[10:11] offset:2048
	global_load_dwordx4 v[92:95], v112, s[10:11] offset:3072
	s_add_u32 s6, s10, 0x200000
	s_addc_u32 s7, s11, 0
	global_load_dwordx4 v[96:99], v112, s[6:7] offset:0
	global_load_dwordx4 v[100:103], v112, s[6:7] offset:1024
	global_load_dwordx4 v[104:107], v112, s[6:7] offset:2048
	global_load_dwordx4 v[108:111], v112, s[6:7] offset:3072
	s_add_u32 s6, s10, 0x400000
	s_addc_u32 s7, s11, 0
	global_load_dwordx4 v[128:131], v112, s[6:7] offset:0
	global_load_dwordx4 v[132:135], v112, s[6:7] offset:1024
	global_load_dwordx4 v[136:139], v112, s[6:7] offset:2048
	global_load_dwordx4 v[140:143], v112, s[6:7] offset:3072
	s_waitcnt vmcnt(8)
	v_pk_add_f32 v[32:33], v[32:33], v[80:81]
	v_pk_add_f32 v[34:35], v[34:35], v[82:83]
	v_pk_add_f32 v[36:37], v[36:37], v[84:85]
	v_pk_add_f32 v[38:39], v[38:39], v[86:87]
	v_pk_add_f32 v[40:41], v[40:41], v[88:89]
	v_pk_add_f32 v[42:43], v[42:43], v[90:91]
	v_pk_add_f32 v[44:45], v[44:45], v[92:93]
	v_pk_add_f32 v[46:47], v[46:47], v[94:95]
	s_waitcnt vmcnt(4)
	v_pk_add_f32 v[32:33], v[32:33], v[96:97]
	v_pk_add_f32 v[34:35], v[34:35], v[98:99]
	v_pk_add_f32 v[36:37], v[36:37], v[100:101]
	v_pk_add_f32 v[38:39], v[38:39], v[102:103]
	v_pk_add_f32 v[40:41], v[40:41], v[104:105]
	v_pk_add_f32 v[42:43], v[42:43], v[106:107]
	v_pk_add_f32 v[44:45], v[44:45], v[108:109]
	v_pk_add_f32 v[46:47], v[46:47], v[110:111]
	s_waitcnt vmcnt(0)
	v_pk_add_f32 v[32:33], v[32:33], v[128:129]
	v_pk_add_f32 v[34:35], v[34:35], v[130:131]
	v_pk_add_f32 v[36:37], v[36:37], v[132:133]
	v_pk_add_f32 v[38:39], v[38:39], v[134:135]
	v_pk_add_f32 v[40:41], v[40:41], v[136:137]
	v_pk_add_f32 v[42:43], v[42:43], v[138:139]
	v_pk_add_f32 v[44:45], v[44:45], v[140:141]
	v_pk_add_f32 v[46:47], v[46:47], v[142:143]

; __device__ __forceinline__ void norm_phase(KP P, const float* g, const float* MODl, int shc, int scc, bool from_input, int npart) {
;     ...
;                 if (t >= SEQ && npart > 0) {
;                     const float4* pp = (const float4*)(P->ws + WS_PART) + (size_t)(b * CTXL + (t - SEQ)) * 256 + lane;
;                     for (int q = 0; q < npart; ++q) {
; #pragma unroll
;                         for (int j = 0; j < 4; ++j) { const float4 a = pp[(size_t)q * 512 * 256 + 64 * j]; v[u][j].x += a.x; v[u][j].y += a.y; v[u][j].z += a.z; v[u][j].w += a.w; } } }
.Lnm_fh3_pone:
	s_cmp_eq_u32 s31, 0
	s_cbranch_scc1 .Lnm_fh3_pdone
	global_load_dwordx4 v[80:83], v112, s[10:11] offset:0
	global_load_dwordx4 v[84:87], v112, s[10:11] offset:1024
	global_load_dwordx4 v[88:91], v112, s[10:11] offset:2048
	global_load_dwordx4 v[92:95], v112, s[10:11] offset:3072
	s_waitcnt vmcnt(0)
	v_pk_add_f32 v[48:49], v[48:49], v[80:81]
	v_pk_add_f32 v[50:51], v[50:51], v[82:83]
	v_pk_add_f32 v[52:53], v[52:53], v[84:85]
	v_pk_add_f32 v[54:55], v[54:55], v[86:87]
	v_pk_add_f32 v[56:57], v[56:57], v[88:89]
	v_pk_add_f32 v[58:59], v[58:59], v[90:91]
	v_pk_add_f32 v[60:61], v[60:61], v[92:93]
	v_pk_add_f32 v[62:63], v[62:63], v[94:95]
	s_branch .Lnm_fh3_pdone
.Lnm_fh3_p10:
	global_load_dwordx4 v[80:83], v112, s[10:11] offset:0
	global_load_dwordx4 v[84:87], v112, s[10:11] offset:1024
	global_load_dwordx4 v[88:91], v112, s[10:11] offset:2048
	global_load_dwordx4 v[92:95], v112, s[10:11] offset:3072
	s_add_u32 s6, s10, 0x200000
	s_addc_u32 s7, s11, 0
	global_load_dwordx4 v[96:99], v112, s[6:7] offset:0
	global_load_dwordx4 v[100:103], v112, s[6:7] offset:1024
	global_load_dwordx4 v[104:107], v112, s[6:7] offset:2048
	global_load_dwordx4 v[108:111], v112, s[6:7] offset:3072
	s_add_u32 s6, s10, 0x400000
	s_addc_u32 s7, s11, 0
	global_load_dwordx4 v[128:131], v112, s[6:7] offset:0
	global_load_dwordx4 v[132:135], v112, s[6:7] offset:1024
	global_load_dwordx4 v[136:139], v112, s[6:7] offset:2048
	global_load_dwordx4 v[140:143], v112, s[6:7] offset:3072
	s_add_u32 s6, s10, 0x600000
	s_addc_u32 s7, s11, 0
	global_load_dwordx4 v[144:147], v112, s[6:7] offset:0
	global_load_dwordx4 v[148:151], v112, s[6:7] offset:1024
	global_load_dwordx4 v[152:155], v112, s[6:7] offset:2048
	global_load_dwordx4 v[156:159], v112, s[6:7] offset:3072
	s_add_u32 s6, s10, 0x800000
	s_addc_u32 s7, s11, 0
	global_load_dwordx4 v[170:173], v112, s[6:7] offset:0
	global_load_dwordx4 v[174:177], v112, s[6:7] offset:1024
	global_load_dwordx4 v[178:181], v112, s[6:7] offset:2048
	global_load_dwordx4 v[182:185], v112, s[6:7] offset:3072
	s_add_u32 s6, s10, 0xa00000
	s_addc_u32 s7, s11, 0
	global_load_dwordx4 v[200:203], v112, s[6:7] offset:0
	global_load_dwordx4 v[204:207], v112, s[6:7] offset:1024
	global_load_dwordx4 v[208:211], v112, s[6:7] offset:2048
	global_load_dwordx4 v[212:215], v112, s[6:7] offset:3072
	s_add_u32 s6, s10, 0xc00000
	s_addc_u32 s7, s11, 0
	global_load_dwordx4 v[226:229], v112, s[6:7] offset:0
	global_load_dwordx4 v[230:233], v112, s[6:7] offset:1024
	global_load_dwordx4 v[234:237], v112, s[6:7] offset:2048
	global_load_dwordx4 v[238:241], v112, s[6:7] offset:3072
	s_waitcnt vmcnt(24)
	v_pk_add_f32 v[48:49], v[48:49], v[80:81]
	v_pk_add_f32 v[50:51], v[50:51], v[82:83]
	v_pk_add_f32 v[52:53], v[52:53], v[84:85]
	v_pk_add_f32 v[54:55], v[54:55], v[86:87]
	v_pk_add_f32 v[56:57], v[56:57], v[88:89]
	v_pk_add_f32 v[58:59], v[58:59], v[90:91]
	v_pk_add_f32 v[60:61], v[60:61], v[92:93]
	v_pk_add_f32 v[62:63], v[62:63], v[94:95]
	s_add_u32 s6, s10, 0xe00000
	s_addc_u32 s7, s11, 0
	global_load_dwordx4 v[80:83], v112, s[6:7] offset:0
	global_load_dwordx4 v[84:87], v112, s[6:7] offset:1024
	global_load_dwordx4 v[88:91], v112, s[6:7] offset:2048
	global_load_dwordx4 v[92:95], v112, s[6:7] offset:3072
	s_waitcnt vmcnt(24)
	v_pk_add_f32 v[48:49], v[48:49], v[96:97]
	v_pk_add_f32 v[50:51], v[50:51], v[98:99]
	v_pk_add_f32 v[52:53], v[52:53], v[100:101]
	v_pk_add_f32 v[54:55], v[54:55], v[102:103]
	v_pk_add_f32 v[56:57], v[56:57], v[104:105]
	v_pk_add_f32 v[58:59], v[58:59], v[106:107]
	v_pk_add_f32 v[60:61], v[60:61], v[108:109]
	v_pk_add_f32 v[62:63], v[62:63], v[110:111]
	s_add_u32 s6, s10, 0x1000000
	s_addc_u32 s7, s11, 0
	global_load_dwordx4 v[96:99], v112, s[6:7] offset:0
	global_load_dwordx4 v[100:103], v112, s[6:7] offset:1024
	global_load_dwordx4 v[104:107], v112, s[6:7] offset:2048
	global_load_dwordx4 v[108:111], v112, s[6:7] offset:3072
	s_waitcnt vmcnt(24)
	v_pk_add_f32 v[48:49], v[48:49], v[128:129]
	v_pk_add_f32 v[50:51], v[50:51], v[130:131]
	v_pk_add_f32 v[52:53], v[52:53], v[132:133]
	v_pk_add_f32 v[54:55], v[54:55], v[134:135]
	v_pk_add_f32 v[56:57], v[56:57], v[136:137]
	v_pk_add_f32 v[58:59], v[58:59], v[138:139]
	v_pk_add_f32 v[60:61], v[60:61], v[140:141]
	v_pk_add_f32 v[62:63], v[62:63], v[142:143]
	s_add_u32 s6, s10, 0x1200000
	s_addc_u32 s7, s11, 0
	global_load_dwordx4 v[128:131], v112, s[6:7] offset:0
	global_load_dwordx4 v[132:135], v112, s[6:7] offset:1024
	global_load_dwordx4 v[136:139], v112, s[6:7] offset:2048
	global_load_dwordx4 v[140:143], v112, s[6:7] offset:3072
	s_waitcnt vmcnt(24)
; __device__ __forceinline__ void norm_phase(KP P, const float* g, const float* MODl, int shc, int scc, bool from_input, int npart) {
;     ...
;                 if (t >= SEQ && npart > 0) {
;                     const float4* pp = (const float4*)(P->ws + WS_PART) + (size_t)(b * CTXL + (t - SEQ)) * 256 + lane;
;                     for (int q = 0; q < npart; ++q) {
; #pragma unroll
;                         for (int j = 0; j < 4; ++j) { const float4 a = pp[(size_t)q * 512 * 256 + 64 * j]; v[u][j].x += a.x; v[u][j].y += a.y; v[u][j].z += a.z; v[u][j].w += a.w; } } }
	v_pk_add_f32 v[48:49], v[48:49], v[144:145]
	v_pk_add_f32 v[50:51], v[50:51], v[146:147]
	v_pk_add_f32 v[52:53], v[52:53], v[148:149]
	v_pk_add_f32 v[54:55], v[54:55], v[150:151]
	v_pk_add_f32 v[56:57], v[56:57], v[152:153]
	v_pk_add_f32 v[58:59], v[58:59], v[154:155]
	v_pk_add_f32 v[60:61], v[60:61], v[156:157]
	v_pk_add_f32 v[62:63], v[62:63], v[158:159]
	s_waitcnt vmcnt(20)
	v_pk_add_f32 v[48:49], v[48:49], v[170:171]
	v_pk_add_f32 v[50:51], v[50:51], v[172:173]
	v_pk_add_f32 v[52:53], v[52:53], v[174:175]
	v_pk_add_f32 v[54:55], v[54:55], v[176:177]
	v_pk_add_f32 v[56:57], v[56:57], v[178:179]
	v_pk_add_f32 v[58:59], v[58:59], v[180:181]
	v_pk_add_f32 v[60:61], v[60:61], v[182:183]
	v_pk_add_f32 v[62:63], v[62:63], v[184:185]
	s_waitcnt vmcnt(16)
	v_pk_add_f32 v[48:49], v[48:49], v[200:201]
	v_pk_add_f32 v[50:51], v[50:51], v[202:203]
	v_pk_add_f32 v[52:53], v[52:53], v[204:205]
	v_pk_add_f32 v[54:55], v[54:55], v[206:207]
	v_pk_add_f32 v[56:57], v[56:57], v[208:209]
	v_pk_add_f32 v[58:59], v[58:59], v[210:211]
	v_pk_add_f32 v[60:61], v[60:61], v[212:213]
	v_pk_add_f32 v[62:63], v[62:63], v[214:215]
	s_waitcnt vmcnt(12)
	v_pk_add_f32 v[48:49], v[48:49], v[226:227]
	v_pk_add_f32 v[50:51], v[50:51], v[228:229]
	v_pk_add_f32 v[52:53], v[52:53], v[230:231]
	v_pk_add_f32 v[54:55], v[54:55], v[232:233]
	v_pk_add_f32 v[56:57], v[56:57], v[234:235]
	v_pk_add_f32 v[58:59], v[58:59], v[236:237]
	v_pk_add_f32 v[60:61], v[60:61], v[238:239]
	v_pk_add_f32 v[62:63], v[62:63], v[240:241]
	s_waitcnt vmcnt(8)
	v_pk_add_f32 v[48:49], v[48:49], v[80:81]
	v_pk_add_f32 v[50:51], v[50:51], v[82:83]
	v_pk_add_f32 v[52:53], v[52:53], v[84:85]
	v_pk_add_f32 v[54:55], v[54:55], v[86:87]
	v_pk_add_f32 v[56:57], v[56:57], v[88:89]
	v_pk_add_f32 v[58:59], v[58:59], v[90:91]
	v_pk_add_f32 v[60:61], v[60:61], v[92:93]
	v_pk_add_f32 v[62:63], v[62:63], v[94:95]
	s_waitcnt vmcnt(4)
	v_pk_add_f32 v[48:49], v[48:49], v[96:97]
	v_pk_add_f32 v[50:51], v[50:51], v[98:99]
	v_pk_add_f32 v[52:53], v[52:53], v[100:101]
	v_pk_add_f32 v[54:55], v[54:55], v[102:103]
	v_pk_add_f32 v[56:57], v[56:57], v[104:105]
	v_pk_add_f32 v[58:59], v[58:59], v[106:107]
	v_pk_add_f32 v[60:61], v[60:61], v[108:109]
	v_pk_add_f32 v[62:63], v[62:63], v[110:111]
	s_waitcnt vmcnt(0)
	v_pk_add_f32 v[48:49], v[48:49], v[128:129]
	v_pk_add_f32 v[50:51], v[50:51], v[130:131]
	v_pk_add_f32 v[52:53], v[52:53], v[132:133]
	v_pk_add_f32 v[54:55], v[54:55], v[134:135]
	v_pk_add_f32 v[56:57], v[56:57], v[136:137]
	v_pk_add_f32 v[58:59], v[58:59], v[138:139]
	v_pk_add_f32 v[60:61], v[60:61], v[140:141]
	v_pk_add_f32 v[62:63], v[62:63], v[142:143]
	s_branch .Lnm_fh3_pdone
.Lnm_fh3_p3:
	global_load_dwordx4 v[80:83], v112, s[10:11] offset:0
	global_load_dwordx4 v[84:87], v112, s[10:11] offset:1024
	global_load_dwordx4 v[88:91], v112, s[10:11] offset:2048
	global_load_dwordx4 v[92:95], v112, s[10:11] offset:3072
	s_add_u32 s6, s10, 0x200000
	s_addc_u32 s7, s11, 0
	global_load_dwordx4 v[96:99], v112, s[6:7] offset:0
	global_load_dwordx4 v[100:103], v112, s[6:7] offset:1024
	global_load_dwordx4 v[104:107], v112, s[6:7] offset:2048
	global_load_dwordx4 v[108:111], v112, s[6:7] offset:3072
	s_add_u32 s6, s10, 0x400000
	s_addc_u32 s7, s11, 0
	global_load_dwordx4 v[128:131], v112, s[6:7] offset:0
	global_load_dwordx4 v[132:135], v112, s[6:7] offset:1024
	global_load_dwordx4 v[136:139], v112, s[6:7] offset:2048
	global_load_dwordx4 v[140:143], v112, s[6:7] offset:3072
	s_waitcnt vmcnt(8)
	v_pk_add_f32 v[48:49], v[48:49], v[80:81]
	v_pk_add_f32 v[50:51], v[50:51], v[82:83]
	v_pk_add_f32 v[52:53], v[52:53], v[84:85]
	v_pk_add_f32 v[54:55], v[54:55], v[86:87]
	v_pk_add_f32 v[56:57], v[56:57], v[88:89]
	v_pk_add_f32 v[58:59], v[58:59], v[90:91]
	v_pk_add_f32 v[60:61], v[60:61], v[92:93]
	v_pk_add_f32 v[62:63], v[62:63], v[94:95]
	s_waitcnt vmcnt(4)
	v_pk_add_f32 v[48:49], v[48:49], v[96:97]
	v_pk_add_f32 v[50:51], v[50:51], v[98:99]
	v_pk_add_f32 v[52:53], v[52:53], v[100:101]
	v_pk_add_f32 v[54:55], v[54:55], v[102:103]
	v_pk_add_f32 v[56:57], v[56:57], v[104:105]
	v_pk_add_f32 v[58:59], v[58:59], v[106:107]
	v_pk_add_f32 v[60:61], v[60:61], v[108:109]
	v_pk_add_f32 v[62:63], v[62:63], v[110:111]
	s_waitcnt vmcnt(0)
	v_pk_add_f32 v[48:49], v[48:49], v[128:129]
	v_pk_add_f32 v[50:51], v[50:51], v[130:131]
	v_pk_add_f32 v[52:53], v[52:53], v[132:133]
	v_pk_add_f32 v[54:55], v[54:55], v[134:135]
	v_pk_add_f32 v[56:57], v[56:57], v[136:137]
	v_pk_add_f32 v[58:59], v[58:59], v[138:139]
	v_pk_add_f32 v[60:61], v[60:61], v[140:141]
	v_pk_add_f32 v[62:63], v[62:63], v[142:143]
